# P2 light pass: the two wave_sum bpermute chains interleaved
# speedup vs baseline: 1.0068x; 1.0029x over previous
.LBB0_374:
	s_or_b64 exec, exec, s[2:3]
	s_waitcnt vmcnt(0)
	v_lshlrev_b32_e32 v94, 16, v24
	v_and_b32_e32 v95, 0xffff0000, v24
	v_lshlrev_b32_e32 v82, 16, v25
	v_and_b32_e32 v83, 0xffff0000, v25
	v_lshlrev_b32_e32 v80, 16, v26
	v_and_b32_e32 v81, 0xffff0000, v26
	v_lshlrev_b32_e32 v24, 16, v27
	v_and_b32_e32 v25, 0xffff0000, v27
	v_lshlrev_b32_e32 v26, 16, v8
	v_and_b32_e32 v27, 0xffff0000, v8
	v_lshlrev_b32_e32 v8, 16, v9
	v_and_b32_e32 v9, 0xffff0000, v9
	v_lshlrev_b32_e32 v96, 16, v4
	v_and_b32_e32 v97, 0xffff0000, v4
	v_pk_add_f32 v[8:9], v[82:83], v[8:9]
	v_lshlrev_b32_e32 v4, 16, v5
	v_and_b32_e32 v5, 0xffff0000, v5
	v_pk_add_f32 v[4:5], v[8:9], v[4:5]
	v_lshlrev_b32_e32 v8, 16, v21
	v_and_b32_e32 v9, 0xffff0000, v21
	v_pk_add_f32 v[4:5], v[4:5], v[8:9]
	v_lshlrev_b32_e32 v8, 16, v13
	v_and_b32_e32 v9, 0xffff0000, v13
	v_pk_add_f32 v[4:5], v[4:5], v[8:9]
	v_lshlrev_b32_e32 v8, 16, v37
	v_and_b32_e32 v9, 0xffff0000, v37
	v_pk_add_f32 v[26:27], v[94:95], v[26:27]
	v_pk_add_f32 v[4:5], v[4:5], v[8:9]
	v_lshlrev_b32_e32 v8, 16, v29
	v_and_b32_e32 v9, 0xffff0000, v29
	v_pk_add_f32 v[26:27], v[26:27], v[96:97]
	v_lshlrev_b32_e32 v96, 16, v20
	v_and_b32_e32 v97, 0xffff0000, v20
	v_pk_add_f32 v[8:9], v[4:5], v[8:9]
	v_lshlrev_b32_e32 v4, 16, v10
	v_and_b32_e32 v5, 0xffff0000, v10
	v_pk_add_f32 v[26:27], v[26:27], v[96:97]
	v_lshlrev_b32_e32 v96, 16, v12
	v_and_b32_e32 v97, 0xffff0000, v12
	v_pk_add_f32 v[4:5], v[80:81], v[4:5]
	v_lshlrev_b32_e32 v12, 16, v6
	v_and_b32_e32 v13, 0xffff0000, v6
	v_pk_add_f32 v[4:5], v[4:5], v[12:13]
	v_lshlrev_b32_e32 v12, 16, v22
	v_and_b32_e32 v13, 0xffff0000, v22
	v_pk_add_f32 v[4:5], v[4:5], v[12:13]
	v_lshlrev_b32_e32 v12, 16, v14
	v_and_b32_e32 v13, 0xffff0000, v14
	v_pk_add_f32 v[4:5], v[4:5], v[12:13]
	v_lshlrev_b32_e32 v12, 16, v38
	v_and_b32_e32 v13, 0xffff0000, v38
	v_pk_add_f32 v[4:5], v[4:5], v[12:13]
	v_lshlrev_b32_e32 v12, 16, v30
	v_and_b32_e32 v13, 0xffff0000, v30
	v_pk_add_f32 v[12:13], v[4:5], v[12:13]
	v_lshlrev_b32_e32 v4, 16, v11
	v_and_b32_e32 v5, 0xffff0000, v11
	v_pk_add_f32 v[4:5], v[24:25], v[4:5]
	v_lshlrev_b32_e32 v6, 16, v7
	v_and_b32_e32 v7, 0xffff0000, v7
	v_pk_add_f32 v[4:5], v[4:5], v[6:7]
	v_lshlrev_b32_e32 v6, 16, v23
	v_and_b32_e32 v7, 0xffff0000, v23
	v_pk_add_f32 v[4:5], v[4:5], v[6:7]
	v_lshlrev_b32_e32 v6, 16, v15
	v_and_b32_e32 v7, 0xffff0000, v15
	v_lshlrev_b32_e32 v14, 16, v50
	v_and_b32_e32 v15, 0xffff0000, v50
	v_cvt_f32_i32_e32 v50, v92
	v_lshlrev_b32_e32 v20, 16, v51
	v_and_b32_e32 v21, 0xffff0000, v51
	v_pk_add_f32 v[26:27], v[26:27], v[96:97]
	v_div_scale_f32 v51, s[2:3], v50, v50, 1.0
	v_lshlrev_b32_e32 v96, 16, v36
	v_and_b32_e32 v97, 0xffff0000, v36
	v_pk_add_f32 v[4:5], v[4:5], v[6:7]
	v_lshlrev_b32_e32 v6, 16, v39
	v_and_b32_e32 v7, 0xffff0000, v39
	v_lshlrev_b32_e32 v38, 16, v60
	v_and_b32_e32 v39, 0xffff0000, v60
	v_rcp_f32_e32 v60, v51
	v_pk_add_f32 v[26:27], v[26:27], v[96:97]
	v_lshlrev_b32_e32 v96, 16, v28
	v_and_b32_e32 v97, 0xffff0000, v28
	v_pk_add_f32 v[4:5], v[4:5], v[6:7]
	v_lshlrev_b32_e32 v6, 16, v31
	v_and_b32_e32 v7, 0xffff0000, v31
	v_pk_add_f32 v[26:27], v[26:27], v[96:97]
	v_pk_add_f32 v[10:11], v[4:5], v[6:7]
	v_lshlrev_b32_e32 v4, 16, v48
	v_and_b32_e32 v5, 0xffff0000, v48
	v_lshlrev_b32_e32 v6, 16, v49
	v_and_b32_e32 v7, 0xffff0000, v49
	v_lshlrev_b32_e32 v22, 16, v44
	v_and_b32_e32 v23, 0xffff0000, v44
	v_lshlrev_b32_e32 v28, 16, v45
	v_and_b32_e32 v29, 0xffff0000, v45
	v_pk_add_f32 v[4:5], v[26:27], v[4:5]
	v_pk_add_f32 v[6:7], v[8:9], v[6:7]
	v_lshlrev_b32_e32 v44, 16, v61
	v_and_b32_e32 v45, 0xffff0000, v61
	v_fma_f32 v61, -v51, v60, 1.0
	v_pk_add_f32 v[4:5], v[4:5], v[22:23]
	v_pk_add_f32 v[6:7], v[6:7], v[28:29]
	v_fmac_f32_e32 v60, v61, v60
	v_div_scale_f32 v61, vcc, 1.0, v50, 1.0
	v_pk_add_f32 v[4:5], v[4:5], v[38:39]
	v_lshlrev_b32_e32 v22, 16, v16
	v_and_b32_e32 v23, 0xffff0000, v16
	v_pk_add_f32 v[6:7], v[6:7], v[44:45]
	v_lshlrev_b32_e32 v8, 16, v17
	v_and_b32_e32 v9, 0xffff0000, v17
	v_lshlrev_b32_e32 v30, 16, v46
	v_and_b32_e32 v31, 0xffff0000, v46
	v_lshlrev_b32_e32 v36, 16, v47
	v_and_b32_e32 v37, 0xffff0000, v47
	v_lshlrev_b32_e32 v46, 16, v62
	v_and_b32_e32 v47, 0xffff0000, v62
	v_mul_f32_e32 v62, v61, v60
	v_pk_add_f32 v[4:5], v[4:5], v[22:23]
	v_lshlrev_b32_e32 v22, 16, v40
	v_and_b32_e32 v23, 0xffff0000, v40
	v_pk_add_f32 v[6:7], v[6:7], v[8:9]
	v_lshlrev_b32_e32 v8, 16, v41
	v_and_b32_e32 v9, 0xffff0000, v41
	v_lshlrev_b32_e32 v48, 16, v63
	v_and_b32_e32 v49, 0xffff0000, v63
	v_fma_f32 v63, -v51, v62, v61
	v_pk_add_f32 v[4:5], v[4:5], v[22:23]
	v_lshlrev_b32_e32 v22, 16, v32
	v_and_b32_e32 v23, 0xffff0000, v32
	v_pk_add_f32 v[6:7], v[6:7], v[8:9]
	v_lshlrev_b32_e32 v8, 16, v33
	v_and_b32_e32 v9, 0xffff0000, v33
	v_fmac_f32_e32 v62, v63, v60
	v_pk_add_f32 v[4:5], v[4:5], v[22:23]
	v_lshlrev_b32_e32 v22, 16, v56
	v_and_b32_e32 v23, 0xffff0000, v56
	v_pk_add_f32 v[6:7], v[6:7], v[8:9]
	v_lshlrev_b32_e32 v8, 16, v57
	v_and_b32_e32 v9, 0xffff0000, v57
	v_fma_f32 v51, -v51, v62, v61
	v_pk_add_f32 v[4:5], v[4:5], v[22:23]
	v_lshlrev_b32_e32 v22, 16, v52
	v_and_b32_e32 v23, 0xffff0000, v52
	v_pk_add_f32 v[6:7], v[6:7], v[8:9]
	v_lshlrev_b32_e32 v8, 16, v53
	v_and_b32_e32 v9, 0xffff0000, v53
	v_div_fmas_f32 v51, v51, v60, v62
	v_pk_add_f32 v[4:5], v[4:5], v[22:23]
	v_lshlrev_b32_e32 v22, 16, v64
	v_and_b32_e32 v23, 0xffff0000, v64
	v_pk_add_f32 v[6:7], v[6:7], v[8:9]
	v_lshlrev_b32_e32 v8, 16, v65
	v_and_b32_e32 v9, 0xffff0000, v65
	v_div_fixup_f32 v50, v51, v50, 1.0
	v_pk_add_f32 v[4:5], v[4:5], v[22:23]
	v_pk_add_f32 v[6:7], v[6:7], v[8:9]
	v_pk_fma_f32 v[4:5], v[50:51], v[4:5], v[94:95] op_sel_hi:[0,1,1] neg_lo:[0,0,1] neg_hi:[0,0,1]
	v_pk_fma_f32 v[6:7], v[50:51], v[6:7], v[82:83] op_sel_hi:[0,1,1] neg_lo:[0,0,1] neg_hi:[0,0,1]
	v_cvt_pk_bf16_f32 v4, v4, v5
	v_cvt_pk_bf16_f32 v5, v6, v7
	v_pk_add_f32 v[6:7], v[12:13], v[14:15]
	v_lshlrev_b32_e32 v8, 16, v18
	v_pk_add_f32 v[6:7], v[6:7], v[30:31]
	v_and_b32_e32 v9, 0xffff0000, v18
	v_pk_add_f32 v[6:7], v[6:7], v[46:47]
	s_add_i32 s6, s6, s4
	v_pk_add_f32 v[6:7], v[6:7], v[8:9]
	v_lshlrev_b32_e32 v8, 16, v42
	v_and_b32_e32 v9, 0xffff0000, v42
	v_pk_add_f32 v[6:7], v[6:7], v[8:9]
	v_lshlrev_b32_e32 v8, 16, v34
	v_and_b32_e32 v9, 0xffff0000, v34
	v_pk_add_f32 v[6:7], v[6:7], v[8:9]
	v_lshlrev_b32_e32 v8, 16, v58
	v_and_b32_e32 v9, 0xffff0000, v58
	v_pk_add_f32 v[6:7], v[6:7], v[8:9]
	v_lshlrev_b32_e32 v8, 16, v54
	v_and_b32_e32 v9, 0xffff0000, v54
	v_pk_add_f32 v[6:7], v[6:7], v[8:9]
	v_lshlrev_b32_e32 v8, 16, v66
	v_and_b32_e32 v9, 0xffff0000, v66
	v_pk_add_f32 v[6:7], v[6:7], v[8:9]
	v_pk_add_f32 v[8:9], v[10:11], v[20:21]
	v_lshlrev_b32_e32 v10, 16, v19
	v_pk_add_f32 v[8:9], v[8:9], v[36:37]
	v_and_b32_e32 v11, 0xffff0000, v19
	v_pk_add_f32 v[8:9], v[8:9], v[48:49]
	v_pk_fma_f32 v[6:7], v[50:51], v[6:7], v[80:81] op_sel_hi:[0,1,1] neg_lo:[0,0,1] neg_hi:[0,0,1]
	v_pk_add_f32 v[8:9], v[8:9], v[10:11]
	v_lshlrev_b32_e32 v10, 16, v43
	v_and_b32_e32 v11, 0xffff0000, v43
	v_pk_add_f32 v[8:9], v[8:9], v[10:11]
	v_lshlrev_b32_e32 v10, 16, v35
	v_and_b32_e32 v11, 0xffff0000, v35
	v_pk_add_f32 v[8:9], v[8:9], v[10:11]
	v_lshlrev_b32_e32 v10, 16, v59
	v_and_b32_e32 v11, 0xffff0000, v59
	v_pk_add_f32 v[8:9], v[8:9], v[10:11]
	v_lshlrev_b32_e32 v10, 16, v55
	v_and_b32_e32 v11, 0xffff0000, v55
	v_pk_add_f32 v[8:9], v[8:9], v[10:11]
	v_lshlrev_b32_e32 v10, 16, v67
	v_and_b32_e32 v11, 0xffff0000, v67
	v_pk_add_f32 v[8:9], v[8:9], v[10:11]
	v_cvt_pk_bf16_f32 v6, v6, v7
	v_pk_fma_f32 v[8:9], v[50:51], v[8:9], v[24:25] op_sel_hi:[0,1,1] neg_lo:[0,0,1] neg_hi:[0,0,1]
	v_cvt_pk_bf16_f32 v7, v8, v9
	v_add_co_u32_e32 v8, vcc, s5, v78
	s_add_i32 s2, s6, 15
	s_nop 0
	v_addc_co_u32_e32 v9, vcc, 0, v79, vcc
	global_store_dwordx4 v[8:9], v[4:7], off
	s_cmp_lt_i32 s2, 0x8000
	v_lshl_add_u64 v[76:77], v[76:77], 0, s[14:15]
	v_lshl_add_u64 v[4:5], s[0:1], 0, v[74:75]
	v_add_co_u32_e32 v6, vcc, s16, v4
	v_lshl_add_u64 v[74:75], v[74:75], 0, s[12:13]
	s_nop 0
	v_addc_co_u32_e32 v7, vcc, 0, v5, vcc
	v_mov_b32_e32 v6, v102
	v_mov_b32_e32 v7, v103
	v_lshlrev_b32_e32 v106, 16, v104
	v_and_b32_e32 v107, 0xffff0000, v104
	v_and_b32_e32 v9, 0xffff0000, v7
	v_and_b32_e32 v11, 0xffff0000, v6
	v_lshlrev_b32_e32 v8, 16, v7
	v_lshlrev_b32_e32 v10, 16, v6
	v_mov_b32_e32 v12, v11
	v_mov_b32_e32 v13, v9
	v_mov_b32_e32 v6, v10
	v_mov_b32_e32 v7, v8
	v_pk_mul_f32 v[12:13], v[12:13], v[12:13]
	s_nop 0
	v_pk_fma_f32 v[6:7], v[6:7], v[6:7], v[12:13]
	s_nop 0
	v_add_f32_e32 v6, v6, v7
	v_pk_mul_f32 v[108:109], v[106:107], v[106:107]
	s_nop 0
	v_add_f32_e32 v108, v108, v109
	ds_bpermute_b32 v7, v85, v6
	ds_bpermute_b32 v109, v85, v108
	s_waitcnt lgkmcnt(0)
	v_add_f32_e32 v6, v6, v7
	v_add_f32_e32 v108, v108, v109
	ds_bpermute_b32 v7, v86, v6
	ds_bpermute_b32 v109, v86, v108
	s_waitcnt lgkmcnt(0)
	v_add_f32_e32 v6, v6, v7
	v_add_f32_e32 v108, v108, v109
	ds_bpermute_b32 v7, v87, v6
	ds_bpermute_b32 v109, v87, v108
	s_waitcnt lgkmcnt(0)
	v_add_f32_e32 v6, v6, v7
	v_add_f32_e32 v108, v108, v109
	ds_bpermute_b32 v7, v88, v6
	ds_bpermute_b32 v109, v88, v108
	s_waitcnt lgkmcnt(0)
	v_add_f32_e32 v6, v6, v7
	v_add_f32_e32 v108, v108, v109
	ds_bpermute_b32 v7, v89, v6
	ds_bpermute_b32 v109, v89, v108
	s_waitcnt lgkmcnt(0)
	v_add_f32_e32 v6, v6, v7
	v_add_f32_e32 v108, v108, v109
	ds_bpermute_b32 v7, v90, v6
	ds_bpermute_b32 v109, v90, v108
	s_waitcnt lgkmcnt(0)
	v_add_f32_e32 v6, v6, v7
	v_add_f32_e32 v108, v108, v109
	v_fmamk_f32 v6, v6, 0x3b800000, v91
	v_mul_f32_e32 v7, 0x4b800000, v6
	v_cmp_gt_f32_e32 vcc, s17, v6
	s_nop 1
	v_cndmask_b32_e32 v6, v6, v7, vcc
	v_rsq_f32_e32 v6, v6
	s_nop 0
	v_mul_f32_e32 v7, 0x45800000, v6
	v_cndmask_b32_e32 v6, v6, v7, vcc
	v_pk_mul_f32 v[10:11], v[6:7], v[10:11] op_sel_hi:[0,1]
	v_pk_mul_f32 v[6:7], v[6:7], v[8:9] op_sel_hi:[0,1]
	v_pk_mul_f32 v[10:11], v[0:1], v[10:11]
	v_pk_mul_f32 v[6:7], v[2:3], v[6:7]
	v_add_co_u32_e32 v4, vcc, s18, v4
	v_cvt_pk_bf16_f32 v10, v10, v11
	v_cvt_pk_bf16_f32 v11, v6, v7
	v_addc_co_u32_e32 v5, vcc, 0, v5, vcc
	global_store_dwordx2 v[4:5], v[10:11], off
	v_lshl_add_u64 v[4:5], s[0:1], 0, v[72:73]
	v_lshl_add_u64 v[72:73], v[72:73], 0, s[8:9]
	v_fmamk_f32 v108, v108, 0x3c000000, v91
	v_mul_f32_e32 v109, 0x4b800000, v108
	v_cmp_gt_f32_e32 vcc, s17, v108
	s_nop 1
	v_cndmask_b32_e32 v108, v108, v109, vcc
	v_rsq_f32_e32 v108, v108
	s_nop 0
	v_mul_f32_e32 v109, 0x45800000, v108
	v_cndmask_b32_e32 v108, v108, v109, vcc
	v_pk_mul_f32 v[6:7], v[108:109], v[106:107] op_sel_hi:[0,1]
	v_pk_mul_f32 v[6:7], v[68:69], v[6:7]
	v_add_co_u32_e32 v4, vcc, 0x13a00000, v4
	v_cvt_pk_bf16_f32 v6, v6, v7
	s_nop 0
	v_addc_co_u32_e32 v5, vcc, 0, v5, vcc
	global_store_dword v[4:5], v6, off
	s_cbranch_scc0 .LBB0_405
